# cache policy: sc1 (write-through) on ROW1's f32 h2 scratch stores that the router re-reads from L2
# baseline (speedup 1.0000x reference)
; __device__ __forceinline__ void ln_stats(const f32x4 (&v)[4], float& mean, float& rstd) {
;     float s = 0.f;
; #pragma unroll
;     for (int j = 0; j < 4; ++j) s += (v[j].x + v[j].y) + (v[j].z + v[j].w);
;     mean = wsum(s) * (1.f / D);
;     float s2 = 0.f;
; #pragma unroll
;     for (int j = 0; j < 4; ++j) { const f32x4 d = v[j] - mean; s2 += (d.x * d.x + d.y * d.y) + (d.z * d.z + d.w * d.w); }
;     rstd = 1.f / sqrtf(wsum(s2) * (1.f / D) + LN_EPS);
; }
; __device__ __forceinline__ void deepnorm_r(f32x4 (&x)[4], const f32x4 (&y)[4], const f32x4 (&g1)[4], const f32x4 (&lg)[4], const f32x4 (&lb)[4]) {
; #pragma unroll
;     for (int j = 0; j < 4; ++j) x[j] = ALPHA * x[j] + g1[j] * y[j];
;     float mean, rstd; ln_stats(x, mean, rstd);
; #pragma unroll
;     for (int j = 0; j < 4; ++j) x[j] = (x[j] - mean) * rstd * lg[j] + lb[j];
; }
.LBB0_2147:
	v_lshlrev_b32_e32 v164, 16, v152
	v_and_b32_e32 v165, 0xffff0000, v152
	v_lshlrev_b32_e32 v152, 16, v153
	v_and_b32_e32 v153, 0xffff0000, v153
	v_lshlrev_b32_e32 v168, 16, v148
	v_and_b32_e32 v169, 0xffff0000, v148
	v_lshlrev_b32_e32 v148, 16, v149
	v_and_b32_e32 v149, 0xffff0000, v149
	v_lshlrev_b32_e32 v166, 16, v150
	v_and_b32_e32 v167, 0xffff0000, v150
	v_lshlrev_b32_e32 v150, 16, v151
	v_and_b32_e32 v151, 0xffff0000, v151
	v_lshlrev_b32_e32 v170, 16, v146
	v_and_b32_e32 v171, 0xffff0000, v146
	v_lshlrev_b32_e32 v146, 16, v147
	v_and_b32_e32 v147, 0xffff0000, v147
	v_pk_mul_f32 v[164:165], v[94:95], v[164:165]
	v_pk_mul_f32 v[152:153], v[96:97], v[152:153]
	v_pk_mul_f32 v[148:149], v[88:89], v[148:149]
	v_pk_fma_f32 v[80:81], v[80:81], s[16:17], v[152:153] op_sel_hi:[1,0,1]
	v_pk_fma_f32 v[78:79], v[78:79], s[16:17], v[164:165] op_sel_hi:[1,0,1]
	v_pk_mul_f32 v[152:153], v[90:91], v[166:167]
	v_pk_mul_f32 v[150:151], v[92:93], v[150:151]
	v_pk_fma_f32 v[72:73], v[72:73], s[16:17], v[148:149] op_sel_hi:[1,0,1]
	v_pk_mul_f32 v[148:149], v[82:83], v[170:171]
	v_pk_mul_f32 v[146:147], v[84:85], v[146:147]
	v_pk_fma_f32 v[76:77], v[76:77], s[16:17], v[150:151] op_sel_hi:[1,0,1]
	v_pk_fma_f32 v[74:75], v[74:75], s[16:17], v[152:153] op_sel_hi:[1,0,1]
	v_pk_mul_f32 v[150:151], v[86:87], v[168:169]
	v_pk_fma_f32 v[68:69], v[68:69], s[16:17], v[146:147] op_sel_hi:[1,0,1]
	v_pk_fma_f32 v[66:67], v[66:67], s[16:17], v[148:149] op_sel_hi:[1,0,1]
	v_pk_mov_b32 v[146:147], v[78:79], v[80:81] op_sel:[1,0]
	v_mov_b32_e32 v148, v78
	v_mov_b32_e32 v149, v81
	v_pk_fma_f32 v[70:71], v[70:71], s[16:17], v[150:151] op_sel_hi:[1,0,1]
	v_pk_add_f32 v[146:147], v[146:147], v[148:149]
	v_pk_mov_b32 v[148:149], v[74:75], v[76:77] op_sel:[1,0]
	v_mov_b32_e32 v150, v74
	v_mov_b32_e32 v151, v77
	v_pk_add_f32 v[148:149], v[148:149], v[150:151]
	v_add_f32_e32 v146, v146, v147
	v_pk_add_f32 v[148:149], v[148:149], v[148:149] op_sel:[0,1] op_sel_hi:[1,0]
	v_add_f32_e32 v146, 0, v146
	v_add_f32_e32 v150, v70, v71
	v_add_f32_e32 v152, v72, v73
	v_mov_b32_e32 v147, v66
	v_mov_b32_e32 v149, v67
	v_mov_b32_e32 v151, v68
	v_mov_b32_e32 v153, v69
	v_pk_add_f32 v[146:147], v[146:147], v[148:149]
	v_pk_add_f32 v[148:149], v[150:151], v[152:153]
	s_ashr_i32 s27, s26, 31
	v_pk_add_f32 v[146:147], v[146:147], v[148:149]
	s_lshl_b64 s[30:31], s[26:27], 11
	v_add_f32_e32 v146, v146, v147
	ds_bpermute_b32 v147, v135, v146
	s_mov_b32 s7, 0x1e3ce508
	s_waitcnt lgkmcnt(0)
	v_add_f32_e32 v146, v146, v147
	ds_bpermute_b32 v147, v159, v146
	s_waitcnt lgkmcnt(0)
	v_add_f32_e32 v146, v146, v147
	ds_bpermute_b32 v147, v160, v146
	s_waitcnt lgkmcnt(0)
	v_add_f32_e32 v146, v146, v147
	ds_bpermute_b32 v147, v161, v146
	s_waitcnt lgkmcnt(0)
	v_add_f32_e32 v146, v146, v147
	ds_bpermute_b32 v147, v162, v146
	s_waitcnt lgkmcnt(0)
	v_add_f32_e32 v146, v146, v147
	ds_bpermute_b32 v147, v163, v146
	s_waitcnt lgkmcnt(0)
	v_add_f32_e32 v164, v146, v147
	v_fmamk_f32 v79, v164, 0xba800000, v79
	v_fmac_f32_e32 v78, 0xba800000, v164
	v_fmamk_f32 v81, v164, 0xba800000, v81
	v_fmac_f32_e32 v80, 0xba800000, v164
	v_pk_mul_f32 v[146:147], v[80:81], v[80:81]
	v_pk_mul_f32 v[148:149], v[78:79], v[78:79]
	v_fmamk_f32 v75, v164, 0xba800000, v75
	v_pk_mov_b32 v[150:151], v[148:149], v[146:147] op_sel:[1,0]
	v_mov_b32_e32 v149, v147
	v_pk_add_f32 v[146:147], v[150:151], v[148:149]
	v_fmac_f32_e32 v74, 0xba800000, v164
	v_fmamk_f32 v77, v164, 0xba800000, v77
	v_fmac_f32_e32 v76, 0xba800000, v164
	v_pk_add_f32 v[146:147], v[146:147], v[146:147] op_sel_hi:[0,1]
	v_pk_mul_f32 v[148:149], v[76:77], v[76:77]
	v_pk_mul_f32 v[150:151], v[74:75], v[74:75]
	v_fmac_f32_e32 v70, 0xba800000, v164
	v_pk_mov_b32 v[152:153], v[150:151], v[148:149] op_sel:[1,0]
	v_mov_b32_e32 v151, v149
	v_fmamk_f32 v71, v164, 0xba800000, v71
	v_fmac_f32_e32 v72, 0xba800000, v164
	v_mul_f32_e32 v146, v70, v70
	v_pk_add_f32 v[148:149], v[152:153], v[150:151]
	v_fmamk_f32 v73, v164, 0xba800000, v73
	v_pk_fma_f32 v[150:151], v[70:71], v[70:71], v[146:147] op_sel_hi:[1,1,0]
	v_mul_f32_e32 v146, v72, v72
	v_pk_add_f32 v[148:149], v[148:149], v[148:149] op_sel_hi:[0,1]
	v_pk_fma_f32 v[152:153], v[72:73], v[72:73], v[146:147] op_sel_hi:[1,1,0]
	v_fmamk_f32 v69, v164, 0xba800000, v69
	v_fmac_f32_e32 v68, 0xba800000, v164
	v_fmamk_f32 v67, v164, 0xba800000, v67
	v_fmac_f32_e32 v66, 0xba800000, v164
	v_mul_f32_e32 v150, v66, v66
	v_mul_f32_e32 v152, v67, v67
	v_mul_f32_e32 v146, v68, v68
	v_mul_f32_e32 v148, v69, v69
	v_pk_add_f32 v[150:151], v[150:151], v[152:153]
	v_pk_add_f32 v[146:147], v[146:147], v[148:149]
	s_nop 0
	v_pk_add_f32 v[146:147], v[150:151], v[146:147]
	s_nop 0
	v_add_f32_e32 v146, v146, v147
	ds_bpermute_b32 v147, v135, v146
	s_waitcnt lgkmcnt(0)
	v_add_f32_e32 v146, v146, v147
	ds_bpermute_b32 v147, v159, v146
	s_waitcnt lgkmcnt(0)
	v_add_f32_e32 v146, v146, v147
	ds_bpermute_b32 v147, v160, v146
	s_waitcnt lgkmcnt(0)
	v_add_f32_e32 v146, v146, v147
	ds_bpermute_b32 v147, v161, v146
	s_waitcnt lgkmcnt(0)
	v_add_f32_e32 v146, v146, v147
	ds_bpermute_b32 v147, v162, v146
	s_waitcnt lgkmcnt(0)
	v_add_f32_e32 v146, v146, v147
	ds_bpermute_b32 v147, v163, v146
	s_waitcnt lgkmcnt(0)
; __device__ __forceinline__ void ln_stats(const f32x4 (&v)[4], float& mean, float& rstd) {
;     float s = 0.f;
; #pragma unroll
;     for (int j = 0; j < 4; ++j) s += (v[j].x + v[j].y) + (v[j].z + v[j].w);
;     mean = wsum(s) * (1.f / D);
;     float s2 = 0.f;
; #pragma unroll
;     for (int j = 0; j < 4; ++j) { const f32x4 d = v[j] - mean; s2 += (d.x * d.x + d.y * d.y) + (d.z * d.z + d.w * d.w); }
;     rstd = 1.f / sqrtf(wsum(s2) * (1.f / D) + LN_EPS);
; }
; __device__ __forceinline__ void ada_ln_r(f32x4 (&v)[4], const f32x4 (&sc1)[4], const f32x4 (&sh)[4]) {
;     float mean, rstd; ln_stats(v, mean, rstd);
; #pragma unroll
;     for (int j = 0; j < 4; ++j) v[j] = (v[j] - mean) * rstd * sc1[j] + sh[j];
; }
; __device__ __forceinline__ void deepnorm_r(f32x4 (&x)[4], const f32x4 (&y)[4], const f32x4 (&g1)[4], const f32x4 (&lg)[4], const f32x4 (&lb)[4]) {
; #pragma unroll
;     for (int j = 0; j < 4; ++j) x[j] = ALPHA * x[j] + g1[j] * y[j];
;     float mean, rstd; ln_stats(x, mean, rstd);
; #pragma unroll
;     for (int j = 0; j < 4; ++j) x[j] = (x[j] - mean) * rstd * lg[j] + lb[j];
; }
	v_add_f32_e32 v146, v146, v147
	v_fmamk_f32 v146, v146, 0x3a800000, v226
	v_mul_f32_e32 v147, 0x4f800000, v146
	v_cmp_gt_f32_e32 vcc, s2, v146
	s_nop 1
	v_cndmask_b32_e32 v146, v146, v147, vcc
	v_sqrt_f32_e32 v147, v146
	s_nop 0
	v_add_u32_e32 v148, -1, v147
	v_fma_f32 v149, -v148, v147, v146
	v_cmp_ge_f32_e64 s[44:45], 0, v149
	v_add_u32_e32 v149, 1, v147
	s_nop 0
	v_cndmask_b32_e64 v148, v147, v148, s[44:45]
	v_fma_f32 v147, -v149, v147, v146
	v_cmp_lt_f32_e64 s[44:45], 0, v147
	s_nop 1
	v_cndmask_b32_e64 v147, v148, v149, s[44:45]
	v_mul_f32_e32 v148, 0x37800000, v147
	v_cndmask_b32_e32 v147, v147, v148, vcc
	v_cmp_class_f32_e32 vcc, v146, v227
	s_nop 1
	v_cndmask_b32_e32 v146, v147, v146, vcc
	v_div_scale_f32 v147, s[4:5], v146, v146, 1.0
	v_rcp_f32_e32 v148, v147
	s_nop 0
	v_fma_f32 v149, -v147, v148, 1.0
	v_fmac_f32_e32 v148, v149, v148
	v_div_scale_f32 v149, vcc, 1.0, v146, 1.0
	v_mul_f32_e32 v150, v149, v148
	v_fma_f32 v151, -v147, v150, v149
	v_fmac_f32_e32 v150, v151, v148
	v_fma_f32 v147, -v147, v150, v149
	v_div_fmas_f32 v147, v147, v148, v150
	v_div_fixup_f32 v146, v147, v146, 1.0
	v_pk_mul_f32 v[78:79], v[78:79], v[146:147] op_sel_hi:[1,0]
	v_pk_mul_f32 v[80:81], v[80:81], v[146:147] op_sel_hi:[1,0]
	v_pk_fma_f32 v[78:79], v[18:19], v[78:79], v[34:35]
	v_pk_fma_f32 v[80:81], v[20:21], v[80:81], v[36:37]
	v_pk_mul_f32 v[74:75], v[74:75], v[146:147] op_sel_hi:[1,0]
	v_pk_mul_f32 v[76:77], v[76:77], v[146:147] op_sel_hi:[1,0]
	v_pk_mul_f32 v[70:71], v[70:71], v[146:147] op_sel_hi:[1,0]
	v_pk_mul_f32 v[68:69], v[68:69], v[146:147] op_sel_hi:[1,0]
	v_pk_fma_f32 v[76:77], v[24:25], v[76:77], v[40:41]
	v_pk_fma_f32 v[74:75], v[22:23], v[74:75], v[38:39]
	v_pk_mul_f32 v[72:73], v[72:73], v[146:147] op_sel_hi:[1,0]
	v_pk_fma_f32 v[150:151], v[26:27], v[70:71], v[42:43]
	v_pk_mul_f32 v[66:67], v[66:67], v[146:147] op_sel_hi:[1,0]
	v_pk_fma_f32 v[146:147], v[32:33], v[68:69], v[48:49]
	v_pk_mov_b32 v[68:69], v[78:79], v[80:81] op_sel:[1,0]
	v_mov_b32_e32 v70, v78
	v_mov_b32_e32 v71, v81
	v_pk_fma_f32 v[148:149], v[28:29], v[72:73], v[44:45]
	v_pk_add_f32 v[68:69], v[68:69], v[70:71]
	v_pk_mov_b32 v[70:71], v[74:75], v[76:77] op_sel:[1,0]
	v_mov_b32_e32 v72, v74
	v_mov_b32_e32 v73, v77
	v_pk_add_f32 v[70:71], v[70:71], v[72:73]
	v_pk_fma_f32 v[66:67], v[30:31], v[66:67], v[46:47]
	v_add_f32_e32 v68, v68, v69
	v_pk_add_f32 v[70:71], v[70:71], v[70:71] op_sel_hi:[0,1]
	v_add_f32_e32 v69, 0, v68
	v_add_f32_e32 v73, v150, v151
	v_add_f32_e32 v153, v148, v149
	v_mov_b32_e32 v72, v66
	v_mov_b32_e32 v152, v67
	v_mov_b32_e32 v70, v146
	v_mov_b32_e32 v68, v147
	v_pk_add_f32 v[72:73], v[72:73], v[152:153]
	v_pk_add_f32 v[68:69], v[70:71], v[68:69]
	v_cvt_pk_bf16_f32 v152, v78, v79
	v_cvt_pk_bf16_f32 v153, v80, v81
	v_cvt_pk_bf16_f32 v164, v74, v75
	v_cvt_pk_bf16_f32 v165, v76, v77
	v_cvt_pk_bf16_f32 v166, v150, v151
	s_nop 0
	v_pk_add_f32 v[68:69], v[72:73], v[68:69]
	v_cvt_pk_bf16_f32 v167, v148, v149
	v_cvt_pk_bf16_f32 v168, v66, v67
	v_cvt_pk_bf16_f32 v169, v146, v147
	s_nop 0
	v_add_f32_e32 v68, v68, v69
	ds_bpermute_b32 v69, v135, v68
	s_waitcnt lgkmcnt(0)
	v_add_f32_e32 v68, v68, v69
	ds_bpermute_b32 v69, v159, v68
	s_waitcnt lgkmcnt(0)
	v_add_f32_e32 v68, v68, v69
	ds_bpermute_b32 v69, v160, v68
	s_waitcnt lgkmcnt(0)
	v_add_f32_e32 v68, v68, v69
	ds_bpermute_b32 v69, v161, v68
	s_waitcnt lgkmcnt(0)
	v_add_f32_e32 v68, v68, v69
	ds_bpermute_b32 v69, v162, v68
	s_waitcnt lgkmcnt(0)
	v_add_f32_e32 v68, v68, v69
	ds_bpermute_b32 v69, v163, v68
	s_waitcnt lgkmcnt(0)
	v_add_f32_e32 v172, v68, v69
	v_fmamk_f32 v79, v172, 0xba800000, v79
	v_fmac_f32_e32 v78, 0xba800000, v172
	v_fmamk_f32 v81, v172, 0xba800000, v81
	v_fmac_f32_e32 v80, 0xba800000, v172
	v_pk_mul_f32 v[68:69], v[80:81], v[80:81]
	v_pk_mul_f32 v[70:71], v[78:79], v[78:79]
	v_fmamk_f32 v75, v172, 0xba800000, v75
	v_pk_mov_b32 v[72:73], v[70:71], v[68:69] op_sel:[1,0]
	v_mov_b32_e32 v71, v69
	v_pk_add_f32 v[68:69], v[72:73], v[70:71]
	v_fmac_f32_e32 v74, 0xba800000, v172
	v_fmamk_f32 v77, v172, 0xba800000, v77
	v_fmac_f32_e32 v76, 0xba800000, v172
	v_pk_add_f32 v[68:69], v[68:69], v[68:69] op_sel_hi:[0,1]
	v_pk_mul_f32 v[70:71], v[76:77], v[76:77]
	v_pk_mul_f32 v[72:73], v[74:75], v[74:75]
	v_fmac_f32_e32 v150, 0xba800000, v172
	v_pk_mov_b32 v[170:171], v[72:73], v[70:71] op_sel:[1,0]
	v_mov_b32_e32 v73, v71
	v_fmamk_f32 v151, v172, 0xba800000, v151
	v_fmac_f32_e32 v148, 0xba800000, v172
	v_mul_f32_e32 v68, v150, v150
	v_pk_add_f32 v[70:71], v[170:171], v[72:73]
	v_fmamk_f32 v149, v172, 0xba800000, v149
	v_pk_fma_f32 v[72:73], v[150:151], v[150:151], v[68:69] op_sel_hi:[1,1,0]
	v_mul_f32_e32 v68, v148, v148
	v_pk_add_f32 v[70:71], v[70:71], v[70:71] op_sel_hi:[0,1]
	v_pk_fma_f32 v[170:171], v[148:149], v[148:149], v[68:69] op_sel_hi:[1,1,0]
	v_fmamk_f32 v147, v172, 0xba800000, v147
	v_fmac_f32_e32 v146, 0xba800000, v172
	v_fmamk_f32 v67, v172, 0xba800000, v67
	v_fmac_f32_e32 v66, 0xba800000, v172
	v_mul_f32_e32 v72, v66, v66
	v_mul_f32_e32 v170, v67, v67
	v_mul_f32_e32 v68, v146, v146
	v_mul_f32_e32 v70, v147, v147
	v_pk_add_f32 v[72:73], v[72:73], v[170:171]
	v_pk_add_f32 v[68:69], v[68:69], v[70:71]
	s_nop 0
	v_pk_add_f32 v[68:69], v[72:73], v[68:69]
	s_nop 0
	v_add_f32_e32 v68, v68, v69
	ds_bpermute_b32 v69, v135, v68
	s_waitcnt lgkmcnt(0)
	v_add_f32_e32 v68, v68, v69
	ds_bpermute_b32 v69, v159, v68
	s_waitcnt lgkmcnt(0)
	v_add_f32_e32 v68, v68, v69
	ds_bpermute_b32 v69, v160, v68
	s_waitcnt lgkmcnt(0)
	v_add_f32_e32 v68, v68, v69
	ds_bpermute_b32 v69, v161, v68
	s_waitcnt lgkmcnt(0)
; __device__ __forceinline__ unsigned pk4_fp8(f32x4 v) { int r = 0; r = __builtin_amdgcn_cvt_pk_fp8_f32(v.x, v.y, r, false); r = __builtin_amdgcn_cvt_pk_fp8_f32(v.z, v.w, r, true); return (unsigned)r; }
; __device__ __forceinline__ void ada_ln_r(f32x4 (&v)[4], const f32x4 (&sc1)[4], const f32x4 (&sh)[4]) {
;     float mean, rstd; ln_stats(v, mean, rstd);
; #pragma unroll
;     for (int j = 0; j < 4; ++j) v[j] = (v[j] - mean) * rstd * sc1[j] + sh[j];
; __device__ __forceinline__ void phase_row1(const Frame& F, int l) {
;     ...
;             store_row_bf16((bf16*)(F.ws + WS_XB) + (size_t)row * D, lane, x);
;             ada_ln_r(x, sc1, sh);
;             store_row(H32 + (size_t)row * D, lane, x);
;             {
;                 float am = 0.f;
; #pragma unroll
;                 for (int j = 0; j < 4; ++j) am = fmaxf(am, fmaxf(fmaxf(fabsf(x[j].x), fabsf(x[j].y)), fmaxf(fabsf(x[j].z), fabsf(x[j].w))));
;                 am = fmaxf(wmaxf(am), 1e-20f);
;                 const float qs = 224.f / am;
;                 unsigned char* hq = (unsigned char*)(F.ws + WS_HQ) + (size_t)row * D;
; #pragma unroll
;                 for (int j = 0; j < 4; ++j) *(unsigned*)(hq + 256 * j + 4 * lane) = pk4_fp8(x[j] * qs);
;                 if (lane == 0) ((float*)(F.ws + WS_HS))[row] = am * (1.f / 224.f);
	v_add_f32_e32 v68, v68, v69
	ds_bpermute_b32 v69, v162, v68
	s_waitcnt lgkmcnt(0)
	v_add_f32_e32 v68, v68, v69
	ds_bpermute_b32 v69, v163, v68
	s_waitcnt lgkmcnt(0)
	v_add_f32_e32 v68, v68, v69
	v_fmamk_f32 v68, v68, 0x3a800000, v226
	v_mul_f32_e32 v69, 0x4f800000, v68
	v_cmp_gt_f32_e32 vcc, s2, v68
	s_nop 1
	v_cndmask_b32_e32 v68, v68, v69, vcc
	v_sqrt_f32_e32 v69, v68
	s_nop 0
	v_add_u32_e32 v70, -1, v69
	v_fma_f32 v71, -v70, v69, v68
	v_cmp_ge_f32_e64 s[44:45], 0, v71
	v_add_u32_e32 v71, 1, v69
	s_nop 0
	v_cndmask_b32_e64 v70, v69, v70, s[44:45]
	v_fma_f32 v69, -v71, v69, v68
	v_cmp_lt_f32_e64 s[44:45], 0, v69
	s_nop 1
	v_cndmask_b32_e64 v69, v70, v71, s[44:45]
	v_mul_f32_e32 v70, 0x37800000, v69
	v_cndmask_b32_e32 v69, v69, v70, vcc
	v_cmp_class_f32_e32 vcc, v68, v227
	s_nop 1
	v_cndmask_b32_e32 v68, v69, v68, vcc
	v_div_scale_f32 v69, s[4:5], v68, v68, 1.0
	v_rcp_f32_e32 v70, v69
	s_lshl_b64 s[4:5], s[26:27], 10
	v_fma_f32 v71, -v69, v70, 1.0
	v_fmac_f32_e32 v70, v71, v70
	v_div_scale_f32 v71, vcc, 1.0, v68, 1.0
	v_mul_f32_e32 v72, v71, v70
	v_fma_f32 v73, -v69, v72, v71
	v_fmac_f32_e32 v72, v73, v70
	v_fma_f32 v69, -v69, v72, v71
	v_div_fmas_f32 v69, v69, v70, v72
	v_div_fixup_f32 v170, v69, v68, 1.0
	v_pk_mul_f32 v[70:71], v[80:81], v[170:171] op_sel_hi:[1,0]
	v_pk_mul_f32 v[72:73], v[74:75], v[170:171] op_sel_hi:[1,0]
	v_pk_mul_f32 v[74:75], v[76:77], v[170:171] op_sel_hi:[1,0]
	v_pk_mul_f32 v[68:69], v[78:79], v[170:171] op_sel_hi:[1,0]
	v_pk_fma_f32 v[70:71], v[112:113], v[70:71], v[60:61]
	v_pk_fma_f32 v[74:75], v[108:109], v[74:75], v[52:53]
	v_pk_mul_f32 v[66:67], v[66:67], v[170:171] op_sel_hi:[1,0]
	v_pk_fma_f32 v[68:69], v[110:111], v[68:69], v[58:59]
	v_pk_fma_f32 v[72:73], v[106:107], v[72:73], v[50:51]
	v_pk_mul_f32 v[78:79], v[148:149], v[170:171] op_sel_hi:[1,0]
	v_pk_mul_f32 v[80:81], v[146:147], v[170:171] op_sel_hi:[1,0]
	v_pk_fma_f32 v[146:147], v[98:99], v[66:67], v[62:63]
	v_max_f32_e64 v66, |v70|, |v71|
	v_max_f32_e64 v67, |v74|, |v75|
	v_pk_mul_f32 v[76:77], v[150:151], v[170:171] op_sel_hi:[1,0]
	v_pk_fma_f32 v[78:79], v[104:105], v[78:79], v[56:57]
	v_pk_fma_f32 v[148:149], v[100:101], v[80:81], v[64:65]
	v_max3_f32 v66, |v68|, |v69|, v66
	v_max3_f32 v67, |v72|, |v73|, v67
	v_pk_fma_f32 v[76:77], v[102:103], v[76:77], v[54:55]
	v_max3_f32 v66, v66, 0, v67
	v_max_f32_e64 v67, |v78|, |v79|
	v_max_f32_e64 v80, |v148|, |v149|
	v_max3_f32 v67, |v76|, |v77|, v67
	v_max3_f32 v80, |v146|, |v147|, v80
	v_max3_f32 v66, v66, v67, v80
	ds_bpermute_b32 v67, v135, v66
	s_waitcnt lgkmcnt(0)
	v_max_f32_e32 v67, v67, v67
	v_max_f32_e32 v66, v66, v67
	ds_bpermute_b32 v67, v159, v66
	s_waitcnt lgkmcnt(0)
	v_max_f32_e32 v67, v67, v67
	v_max_f32_e32 v66, v66, v67
	ds_bpermute_b32 v67, v160, v66
	s_waitcnt lgkmcnt(0)
	v_max_f32_e32 v67, v67, v67
	v_max_f32_e32 v66, v66, v67
	ds_bpermute_b32 v67, v161, v66
	s_waitcnt lgkmcnt(0)
	v_max_f32_e32 v67, v67, v67
	v_max_f32_e32 v80, v66, v67
	ds_bpermute_b32 v81, v162, v80
	v_lshl_add_u64 v[66:67], v[116:117], 0, s[30:31]
	global_store_dwordx2 v[66:67], v[152:153], off nt
	global_store_dwordx2 v[66:67], v[164:165], off offset:512 nt
	global_store_dwordx2 v[66:67], v[166:167], off offset:1024 nt
	global_store_dwordx2 v[66:67], v[168:169], off offset:1536 nt
	s_lshl_b64 s[30:31], s[26:27], 12
	s_waitcnt lgkmcnt(0)
	v_max_f32_e32 v81, v81, v81
	v_max_f32_e32 v150, v80, v81
	ds_bpermute_b32 v151, v163, v150
	v_lshl_add_u64 v[80:81], v[114:115], 0, s[30:31]
	global_store_dwordx4 v[80:81], v[68:71], off sc1
	global_store_dwordx4 v[80:81], v[72:75], off offset:1024 sc1
	global_store_dwordx4 v[80:81], v[76:79], off offset:2048 sc1
	global_store_dwordx4 v[80:81], v[146:149], off offset:3072 sc1
	s_waitcnt lgkmcnt(0)
	v_max3_f32 v66, v150, v151, s7
	v_div_scale_f32 v67, s[30:31], v66, v66, s20
	v_rcp_f32_e32 v150, v67
	s_nop 0
	v_fma_f32 v80, -v67, v150, 1.0
	v_fmac_f32_e32 v150, v80, v150
	v_div_scale_f32 v80, vcc, s20, v66, s20
	v_mul_f32_e32 v81, v80, v150
	v_fma_f32 v151, -v67, v81, v80
	v_fmac_f32_e32 v81, v151, v150
	v_fma_f32 v67, -v67, v81, v80
	v_div_fmas_f32 v67, v67, v150, v81
	v_div_fixup_f32 v80, v67, v66, s20
	v_pk_mul_f32 v[68:69], v[68:69], v[80:81] op_sel_hi:[1,0]
	v_mov_b32_e32 v67, 0
	v_cvt_pk_fp8_f32 v67, v68, v69
	v_pk_mul_f32 v[68:69], v[72:73], v[80:81] op_sel_hi:[1,0]
	v_mov_b32_e32 v72, 0
	v_cvt_pk_fp8_f32 v72, v68, v69
	v_pk_mul_f32 v[68:69], v[70:71], v[80:81] op_sel_hi:[1,0]
	v_mov_b32_e32 v70, 0
	v_cvt_pk_fp8_f32 v67, v68, v69 op_sel:[0,0,1]
	v_pk_mul_f32 v[68:69], v[74:75], v[80:81] op_sel_hi:[1,0]
	v_mov_b32_e32 v71, 0
	v_cvt_pk_fp8_f32 v72, v68, v69 op_sel:[0,0,1]
	v_pk_mul_f32 v[68:69], v[76:77], v[80:81] op_sel_hi:[1,0]
	v_lshl_add_u64 v[150:151], v[120:121], 0, s[4:5]
	v_cvt_pk_fp8_f32 v70, v68, v69
	v_pk_mul_f32 v[68:69], v[146:147], v[80:81] op_sel_hi:[1,0]
	s_nop 0
	v_cvt_pk_fp8_f32 v71, v68, v69
	v_pk_mul_f32 v[68:69], v[78:79], v[80:81] op_sel_hi:[1,0]
	s_nop 0
	v_cvt_pk_fp8_f32 v70, v68, v69 op_sel:[0,0,1]
	v_pk_mul_f32 v[68:69], v[148:149], v[80:81] op_sel_hi:[1,0]
	s_nop 0
	v_cvt_pk_fp8_f32 v71, v68, v69 op_sel:[0,0,1]
	global_store_dword v[150:151], v67, off
	global_store_dword v[150:151], v72, off offset:256
	global_store_dword v[150:151], v70, off offset:512
	global_store_dword v[150:151], v71, off offset:768
	s_and_saveexec_b64 s[4:5], s[0:1]
	s_cbranch_execz .LBB0_2149
	s_lshl_b64 s[26:27], s[26:27], 2
	s_add_u32 s26, s54, s26
	v_mul_f32_e32 v66, 0x3b924925, v66
	s_addc_u32 s27, s55, s27
	global_store_dword v199, v66, s[26:27]
